# v97_p3_all_workgroups_attention_first_then_chunkKV
# speedup vs baseline: 1.0139x; 1.0079x over previous
; __device__ __forceinline__ KArgs kargs() { KArgs p = (KArgs)__builtin_amdgcn_kernarg_segment_ptr(); asm volatile("" : "+s"(p)); return p; }
; #define X make_ctx(lds_raw)
;     ...
;     const int fr = X.lane & 15, fq = X.lane >> 4, w = X.wave, i0 = 16 * w;
;     const int per = (1536 + (int)gridDim.x - 1) / (int)gridDim.x, u0 = (int)blockIdx.x * per, u1 = (u0 + per < 1536) ? u0 + per : 1536;
;     int cur_half = 1;
;     for (int unit = u0; unit < u1; ++unit) {
; __global__ void __launch_bounds__(512, 2) fwd_megakernel(Args a_kernarg) {
;     ...
;     for (int step = 0; step < 2; ++step) {
;         if (((step ^ (int)blockIdx.x) & 1) == 0) { KArgs a = kargs(); gla_a1(X, a, a->out, WSP(float, WS_SSQ)); }
;         else attn_mfma(X, kargs());
.LBB0_328:
	s_cmp_lg_u32 s0, 1
	s_mov_b64 s[0:1], -1
	s_cbranch_scc0 .LBB0_337
	v_writelane_b32 v254, s26, 43
	v_mov_b32_e32 v0, v186
	s_nop 0
	v_writelane_b32 v254, s27, 44
	v_readfirstlane_b32 s2, v0
	v_readlane_b32 s6, v254, 53
	v_readlane_b32 s7, v254, 54
	s_and_b64 vcc, exec, s[6:7]
	s_cbranch_vccnz .LBB0_336
; #define LAS __attribute__((address_space(3)))
; #define X make_ctx(lds_raw)
;     bf16_t* proj = (bf16_t*)(a->ws + WS_BIG); const f32x2* rope = (const f32x2*)(a->ws + WS_ROPE); float* lse = (float*)(a->ws + WS_LSE);
;     LAS bf16_t* Qs = (LAS bf16_t*)X.lds; LAS bf16_t* Ks = (LAS bf16_t*)(X.lds + 128 * QP * 2); LAS bf16_t* Vt = (LAS bf16_t*)(X.lds + 384 * QP * 2);
;     const int fr = X.lane & 15, fq = X.lane >> 4, w = X.wave, i0 = 16 * w;
;     const int per = (1536 + (int)gridDim.x - 1) / (int)gridDim.x, u0 = (int)blockIdx.x * per, u1 = (u0 + per < 1536) ? u0 + per : 1536;
;     int cur_half = 1;
;     for (int unit = u0; unit < u1; ++unit) {
;         const int b = unit / 384, rem = unit % 384, h = rem >> 5, pn = rem & 31, g = h >> 2, hg = h & 3;
;         const int r = (g == 0) ? 1 : (g == 1 ? 4 : 16), nblk = 32 / r, p = pn / nblk, n = pn % nblk;
;         const int tb = b * SEQ + p;
;         const bool reuse = (unit > u0) && (n >= 1);
;         if (reuse) cur_half ^= 1;
;         const int prev_half = cur_half ^ 1;
;         __syncthreads();
;         { const int i = X.tid >> 2, c = X.tid & 3; const int t = tb + (128 * n + i) * r; const bf16_t* src = proj + (size_t)t * NMAIN + C_AQ + h * 64 + 16 * c;
;           *(LAS u32x4*)(Qs + i * QP + 16 * c) = *(const u32x4*)src; *(LAS u32x4*)(Qs + i * QP + 16 * c + 8) = *(const u32x4*)(src + 8); }
;         for (int blk = reuse ? 1 : 0; blk < 2; ++blk) {
;             const int half = blk ? cur_half : prev_half;
;             { const int j = X.tid >> 2, c = X.tid & 3; int m = 128 * (n - 1 + blk) + j; m = m < 0 ? 0 : m; const int t = tb + m * r;
;               const bf16_t* src = proj + (size_t)t * NMAIN + C_AK + h * 64 + 16 * c;
;               *(LAS u32x4*)(Ks + (half * 128 + j) * QP + 16 * c) = *(const u32x4*)src; *(LAS u32x4*)(Ks + (half * 128 + j) * QP + 16 * c + 8) = *(const u32x4*)(src + 8); }
; #pragma unroll
;             for (int q = 0; q < 2; ++q) { const int idx = X.tid + 512 * q, j = idx & 127, c = idx >> 7; int m = 128 * (n - 1 + blk) + j; m = m < 0 ? 0 : m; const int t = tb + m * r;
;                 const u32x4 wv = *(const u32x4*)(proj + (size_t)t * NMAIN + C_AV + h * 64 + 8 * c);
	s_load_dwordx2 s[0:1], s[86:87], 0xa0
	v_and_b32_e32 v16, 15, v0
	v_and_b32_e32 v1, 63, v0
	v_bfe_u32 v6, v0, 4, 2
	v_cmp_gt_u32_e64 s[6:7], 16, v1
	s_waitcnt lgkmcnt(0)
	s_add_u32 s48, s0, 0x4f00000
	s_addc_u32 s49, s1, 0
	s_add_u32 s5, s0, 0x200000
	s_addc_u32 s33, s1, 0
	s_ashr_i32 s0, s2, 6
	s_lshl_b32 s1, s0, 4
	s_cmp_lt_u32 s0, 8
	v_or_b32_e32 v5, s1, v16
	s_cselect_b64 s[50:51], -1, 0
	s_and_b32 s2, s1, 0x70
	s_add_i32 s1, s0, 1
	s_cmp_lt_u32 s1, 8
	s_cselect_b64 s[52:53], -1, 0
	s_lshl_b32 s1, s1, 4
	s_and_b32 s3, s1, 0x70
	s_add_i32 s1, s0, 2
	s_cmp_lt_u32 s1, 8
	s_cselect_b64 s[54:55], -1, 0
	s_lshl_b32 s8, s1, 4
	s_and_b32 s24, s8, 0x70
	s_add_i32 s8, s0, 3
	s_cmp_lt_u32 s8, 8
	s_cselect_b64 s[56:57], -1, 0
	s_lshl_b32 s8, s8, 4
	s_and_b32 s25, s8, 0x70
	s_add_i32 s26, s0, 4
	s_cmp_lt_u32 s26, 8
	s_cselect_b64 s[58:59], -1, 0
	s_lshl_b32 s8, s26, 4
	s_and_b32 s27, s8, 0x70
	s_add_i32 s8, s0, 5
	s_cmp_lt_u32 s8, 8
	s_cselect_b64 s[60:61], -1, 0
	s_lshl_b32 s8, s8, 4
	s_and_b32 s38, s8, 0x70
	s_add_i32 s41, s0, 6
	s_cmp_lt_u32 s41, 8
	s_cselect_b64 s[62:63], -1, 0
	s_lshl_b32 s8, s41, 4
	s_and_b32 s42, s8, 0x70
	s_add_i32 s8, s0, 7
	s_cmp_lt_u32 s8, 8
	s_cselect_b64 s[64:65], -1, 0
	s_lshl_b32 s8, s8, 4
	s_and_b32 s43, s8, 0x70
	s_cmp_gt_u32 s0, -9
	s_cselect_b64 s[66:67], -1, 0
	s_cmp_gt_i32 s0, 7
	s_cselect_b64 s[68:69], -1, 0
	s_cmp_gt_i32 s0, 6
	s_cselect_b64 s[70:71], -1, 0
	s_cmp_gt_i32 s0, 5
	s_cselect_b64 s[72:73], -1, 0
	s_cmp_gt_i32 s0, 4
	s_cselect_b64 s[74:75], -1, 0
	s_cmp_gt_i32 s0, 3
	s_cselect_b64 s[76:77], -1, 0
	s_cmp_gt_i32 s0, 2
	s_cselect_b64 s[78:79], -1, 0
	s_cmp_gt_i32 s0, 1
	s_cselect_b64 s[80:81], -1, 0
	s_cmp_gt_i32 s0, 0
	s_cselect_b64 s[82:83], -1, 0
	s_cmp_gt_i32 s0, -1
	s_cselect_b64 s[84:85], -1, 0
	s_min_i32 s44, s0, 14
	s_add_i32 s44, s44, 1
	s_cmp_lt_u32 s44, 8
	s_cselect_b64 s[86:87], -1, 0
	s_lshl_b32 s44, s44, 5
	s_min_i32 s1, s1, 14
	v_mul_lo_u32 v2, v5, s34
	s_lshl_b32 s45, s2, 1
	s_and_b32 s44, s44, 0xe0
	s_add_i32 s1, s1, 1
	v_add_u32_e32 v17, 0, v2
	v_lshlrev_b32_e32 v2, 2, v6
	v_lshlrev_b32_e32 v6, 3, v6
	v_mul_u32_u24_e32 v1, 0x210, v16
	s_cmp_lt_u32 s1, 8
	v_add3_u32 v1, 0, v6, v1
	s_cselect_b64 s[88:89], -1, 0
	s_lshl_b32 s1, s1, 5
	v_add_u32_e32 v6, 0xd800, v1
	s_and_b32 s1, s1, 0xe0
	v_add_u32_e32 v24, s1, v1
	v_add_u32_e32 v26, s1, v6
	s_min_i32 s1, s26, 14
	v_add_u32_e32 v20, s44, v1
	v_add_u32_e32 v22, s44, v6
	s_lshl_b32 s44, s24, 1
	s_add_i32 s1, s1, 1
	s_cmp_lt_u32 s1, 8
	s_cselect_b64 s[90:91], -1, 0
	s_lshl_b32 s1, s1, 5
	s_and_b32 s1, s1, 0xe0
	v_add_u32_e32 v28, s1, v1
	v_add_u32_e32 v32, s1, v6
	s_min_i32 s1, s41, 14
	s_lshl_b32 s26, s27, 1
	s_add_i32 s1, s1, 1
	s_cmp_lt_u32 s1, 8
	s_cselect_b64 s[92:93], -1, 0
	s_lshl_b32 s1, s1, 5
	s_min_i32 s0, s0, 6
	v_add_u32_e32 v27, s26, v1
	v_add_u32_e32 v29, s26, v6
	s_lshl_b32 s26, s42, 1
	s_and_b32 s1, s1, 0xe0
	s_add_i32 s0, s0, 9
	s_cmp_lt_u32 s0, 8
	s_cselect_b64 s[94:95], -1, 0
	s_lshl_b32 s0, s0, 5
	s_and_b32 s0, s0, 0xe0
	v_cmp_lt_i32_e32 vcc, v143, v190
	v_add_u32_e32 v19, s45, v1
	v_add_u32_e32 v23, s44, v1
	v_add_u32_e32 v33, s26, v1
	v_add_u32_e32 v34, s1, v1
	v_add_u32_e32 v37, s0, v1
	v_lshlrev_b32_e32 v1, 4, v0
	v_sub_u32_e32 v8, v16, v2
	v_cndmask_b32_e32 v7, v187, v143, vcc
	v_cmp_lt_i32_e32 vcc, v142, v190
	v_add_u32_e32 v21, s45, v6
	v_add_u32_e32 v25, s44, v6
	v_add_u32_e32 v35, s26, v6
	v_add_u32_e32 v36, s1, v6
	v_add_u32_e32 v38, s0, v6
	v_and_b32_e32 v6, 48, v1
	v_cndmask_b32_e32 v10, v187, v142, vcc
	v_cmp_gt_i32_e64 s[8:9], 1, v8
	v_cmp_gt_i32_e64 s[10:11], 2, v8
	v_cmp_gt_i32_e64 s[12:13], 3, v8
	v_cmp_gt_i32_e64 s[14:15], 4, v8
	v_cmp_lt_i32_e64 s[16:17], -1, v8
	v_cmp_lt_i32_e64 s[18:19], 0, v8
	v_cmp_lt_i32_e64 s[20:21], 1, v8
	v_cmp_lt_i32_e64 s[22:23], 2, v8
	v_ashrrev_i32_e32 v39, 2, v0
	v_lshl_add_u32 v8, v6, 1, 0
	v_lshlrev_b32_e32 v18, 2, v10
	v_mad_u64_u32 v[10:11], s[0:1], v39, s34, v[8:9]
	v_and_b32_e32 v51, 48, v0
	v_and_b32_e32 v11, 0x7f, v0
	v_ashrrev_i32_e32 v1, 4, v0
	v_add_u32_e32 v0, 0x200, v0
	v_ashrrev_i32_e32 v0, 4, v0
	v_and_b32_e32 v12, -8, v1
	s_movk_i32 s0, 0x210
	v_and_b32_e32 v14, -8, v0
	v_add_u32_e32 v4, 0, v51
	v_lshlrev_b32_e32 v7, 2, v7
	s_mov_b32 s40, 1
	v_lshl_add_u32 v40, v11, 1, 0
	v_ashrrev_i32_e32 v13, 31, v12
	v_mul_lo_u32 v41, v12, s0
	v_ashrrev_i32_e32 v15, 31, v14
	v_mul_lo_u32 v42, v14, s0
	v_or_b32_e32 v43, s2, v16
	v_or_b32_e32 v44, s3, v16
	v_or_b32_e32 v45, s24, v16
	v_or_b32_e32 v46, s25, v16
	v_or_b32_e32 v47, s27, v16
	v_or_b32_e32 v48, s38, v16
	v_or_b32_e32 v49, s42, v16
	v_or_b32_e32 v50, s43, v16
	v_add_u32_e32 v51, v17, v51
	v_lshlrev_b32_e32 v16, 1, v2
	s_mov_b32 s98, s30
	s_mul_hi_i32 s24, s98, 0x2aaaaaab
	s_lshr_b32 s25, s24, 31
	s_ashr_i32 s24, s24, 6
	s_add_i32 s24, s24, s25
	s_mul_i32 s25, s24, 0xfffffe80
	s_add_i32 s98, s98, s25
	s_and_b32 s25, s98, 31
	s_ashr_i32 s26, s98, 7
	s_cmp_eq_u32 s26, 1
	s_cselect_b32 s26, 2, 4
	s_cmpk_gt_u32 s98, 0x7f
	s_cselect_b32 s99, s26, 0
	s_lshr_b32 s26, 32, s99
	s_sub_i32 s27, 5, s99
	s_lshr_b32 s27, s25, s27
	s_add_i32 s26, s26, -1
	s_lshl_b32 s24, s24, 12
	s_and_b32 s26, s26, s25
	s_or_b32 s100, s27, s24
	s_lshl_b32 s24, s98, 1
	s_andn2_b32 s24, s24, 63
	s_lshl_b32 s101, s24, 1
	s_lshl_b32 s24, s26, 7
	s_add_i32 s25, s26, -1
	s_lshl_b32 s27, s25, 7
	s_cmp_gt_i32 s25, -1
	s_cselect_b64 vcc, -1, 0
	v_add_u32_e32 v134, s24, v39
	v_add_u32_e32 v135, s27, v39
	v_or_b32_e32 v144, s27, v11
	v_max_i32_e32 v135, 0, v135
	v_cndmask_b32_e32 v144, 0, v144, vcc
	v_lshlrev_b32_e32 v134, s99, v134
	v_lshlrev_b32_e32 v135, s99, v135
	v_lshlrev_b32_e32 v144, s99, v144
	v_add_u32_e32 v134, s100, v134
	v_add_u32_e32 v135, s100, v135
	v_add_u32_e32 v144, s100, v144
	v_mov_b64_e32 v[136:137], s[48:49]
	v_mad_i64_i32 v[138:139], s[24:25], v134, s35, v[136:137]
	v_mad_i64_i32 v[146:147], s[24:25], v135, s35, v[136:137]
	v_mad_i64_i32 v[150:151], s[24:25], v144, s35, v[136:137]
	v_lshl_add_u32 v140, v6, 1, s101
	v_mov_b32_e32 v141, 0
	v_mov_b32_e32 v135, 0
	v_add_u32_e32 v134, 0x1800, v140
	v_add_u32_e32 v140, 0x1e00, v140
	v_lshl_add_u64 v[138:139], v[138:139], 0, v[134:135]
	v_lshl_add_u64 v[146:147], v[146:147], 0, v[140:141]
	v_lshl_add_u32 v134, v12, 1, s101
	v_lshl_add_u32 v140, v14, 1, s101
	v_add_u32_e32 v134, 0x2400, v134
	v_add_u32_e32 v140, 0x2400, v140
	v_lshl_add_u64 v[148:149], v[150:151], 0, v[134:135]
	v_lshl_add_u64 v[150:151], v[150:151], 0, v[140:141]
	global_load_dwordx4 v[110:113], v[138:139], off
	global_load_dwordx4 v[114:117], v[138:139], off offset:16
	global_load_dwordx4 v[118:121], v[146:147], off
	global_load_dwordx4 v[122:125], v[146:147], off offset:16
	global_load_dwordx4 v[126:129], v[148:149], off
	global_load_dwordx4 v[130:133], v[150:151], off
	s_mov_b32 s41, s30
	s_branch .LBB0_332
